# converter chains each FFN weight set (w2,w1,w3) as one continuous tile stream: one pipeline fill per set instead of three
# baseline (speedup 1.0000x reference)
; #define LAS __attribute__((address_space(3)))
; __global__ void __launch_bounds__(NTHR, 2) mega_fwd(Params p) {
;     ...
;     const size_t WSZ = (size_t)DM * DFF;
;     bf16_t* HB = (bf16_t*)(ws + WS_HB); float* RS = (float*)(ws + WS_RS);
;     const float* NG = p.norm_g;
;     if (IN(0)) {
;         convert_w((LAS float*)lds, p.w2, DFF, DM, W2, 0, 0, nullptr, G, bid);
;         convert_w((LAS float*)lds, p.w1, DM, DFF, W13, 1, 0, NG, G, bid);
;         convert_w((LAS float*)lds, p.w3, DM, DFF, W13, 1, 1, NG, G, bid);
;         rope_phase(p.pos, p.inv, ROPE, G, bid);
.LBB0_19:
	v_readlane_b32 s0, v252, 0
	s_add_u32 s38, s82, 0x5800000
	v_readlane_b32 s1, v252, 1
	s_addc_u32 s39, s83, 0
	s_load_dwordx2 s[0:1], s[0:1], 0x10
	s_add_u32 s36, s82, 0xa480000
	s_addc_u32 s37, s83, 0
	s_add_u32 s2, s82, 0x2a980000
	s_addc_u32 s3, s83, 0
	s_waitcnt lgkmcnt(0)
	v_writelane_b32 v252, s0, 7
	s_cmp_lt_i32 s84, 1
	s_nop 0
	v_writelane_b32 v252, s1, 8
	s_cselect_b64 s[0:1], -1, 0
	s_cmp_gt_i32 s85, 0
	s_cselect_b64 s[4:5], -1, 0
	s_and_b64 s[4:5], s[0:1], s[4:5]
	s_andn2_b64 vcc, exec, s[4:5]
	s_cbranch_vccnz .LBB0_61
	s_mov_b32 s98, 0
	s_branch .Lcv_entry
.Lcv_ret_0:
	s_cmpk_lt_i32 s79, 0
	s_cselect_b64 s[0:1], -1, 0
	s_cmpk_gt_i32 s79, -1
	s_mov_b64 s[6:7], -1
	s_cbranch_scc0 .LBB0_22
	s_mov_b64 s[6:7], 0

; #define LAS __attribute__((address_space(3)))
; __global__ void __launch_bounds__(NTHR, 2) mega_fwd(Params p) {
;     ...
;     if (IN(6)) {
;         convert_w((LAS float*)lds, p.w2 + (size_t)1 * WSZ, DFF, DM, W2 + (size_t)DM * DFF, 0, 0, nullptr, G, bid);
;         convert_w((LAS float*)lds, p.w1 + (size_t)1 * WSZ, DM, DFF, W13 + (size_t)2 * DFF * DM, 1, 0, NG + 2 * DM, G, bid);
;         convert_w((LAS float*)lds, p.w3 + (size_t)1 * WSZ, DM, DFF, W13 + (size_t)2 * DFF * DM, 1, 1, NG + 2 * DM, G, bid);
;     }
.Lcv_site_p6:
	s_mov_b32 s98, 5
	s_branch .Lcv_entry
.Lcv_ret_5:
	s_mov_b64 s[0:1], -1

; #define LAS __attribute__((address_space(3)))
; __global__ void __launch_bounds__(NTHR, 2) mega_fwd(Params p) {
;     ...
;         convert_w((LAS float*)lds, p.w2, DFF, DM, W2, 0, 0, nullptr, G, bid);
;         convert_w((LAS float*)lds, p.w1, DM, DFF, W13, 1, 0, NG, G, bid);
;         convert_w((LAS float*)lds, p.w3, DM, DFF, W13, 1, 1, NG, G, bid);
;     ...
;         convert_w((LAS float*)lds, p.w2 + (size_t)1 * WSZ, DFF, DM, W2 + (size_t)DM * DFF, 0, 0, nullptr, G, bid);
;         convert_w((LAS float*)lds, p.w1 + (size_t)1 * WSZ, DM, DFF, W13 + (size_t)2 * DFF * DM, 1, 0, NG + 2 * DM, G, bid);
;         convert_w((LAS float*)lds, p.w3 + (size_t)1 * WSZ, DM, DFF, W13 + (size_t)2 * DFF * DM, 1, 1, NG + 2 * DM, G, bid);
.Lcv_entry:
	v_writelane_b32 v253, s0, 0
	v_writelane_b32 v253, s1, 1
	v_writelane_b32 v253, s2, 2
	v_writelane_b32 v253, s3, 3
	v_writelane_b32 v253, s4, 4
	v_writelane_b32 v253, s5, 5
	v_writelane_b32 v253, s6, 6
	v_writelane_b32 v253, s7, 7
	v_writelane_b32 v253, s8, 8
	v_writelane_b32 v253, s9, 9
	v_writelane_b32 v253, s10, 10
	v_writelane_b32 v253, s11, 11
	v_writelane_b32 v253, s12, 12
	v_writelane_b32 v253, s13, 13
	v_writelane_b32 v253, s14, 14
	v_writelane_b32 v253, s15, 15
	v_writelane_b32 v253, s16, 16
	v_writelane_b32 v253, s17, 17
	v_writelane_b32 v253, s18, 18
	v_writelane_b32 v253, s19, 19
	v_writelane_b32 v253, s20, 20
	v_writelane_b32 v253, s21, 21
	v_writelane_b32 v253, s22, 22
	v_writelane_b32 v253, s23, 23
	v_writelane_b32 v253, s24, 24
	v_writelane_b32 v253, s25, 25
	v_writelane_b32 v253, s26, 26
	v_writelane_b32 v253, s27, 27
	v_writelane_b32 v253, s28, 28
	v_writelane_b32 v253, s29, 29
	v_writelane_b32 v253, s30, 30
	v_writelane_b32 v253, s31, 31
	v_writelane_b32 v253, s32, 32
	v_writelane_b32 v253, s33, 33
	v_writelane_b32 v253, s34, 34
	v_writelane_b32 v253, s35, 35
	v_writelane_b32 v253, s36, 36
	v_writelane_b32 v253, s37, 37
	v_writelane_b32 v253, s38, 38
	v_writelane_b32 v253, s39, 39
	v_readlane_b32 s0, v252, 0
	v_readlane_b32 s1, v252, 1
	s_cmp_eq_u32 s98, 0
	s_cbranch_scc1 .Lcv_par_0
	s_cmp_eq_u32 s98, 3
	s_cbranch_scc1 .Lcv_par_3
	s_cmp_eq_u32 s98, 4
	s_cbranch_scc1 .Lcv_par_4
	s_cmp_eq_u32 s98, 5
	s_cbranch_scc1 .Lcv_par_5
	s_cmp_eq_u32 s98, 8
	s_cbranch_scc1 .Lcv_par_8
	s_cmp_eq_u32 s98, 11
	s_cbranch_scc1 .Lcv_par_11
	s_cmp_eq_u32 s98, 12
	s_cbranch_scc1 .Lcv_par_12
	s_cmp_eq_u32 s98, 13
	s_cbranch_scc1 .Lcv_par_13
	s_branch .Lcv_par_0
.Lcv_par_0:
	s_load_dwordx2 s[32:33], s[0:1], 0x28
	s_load_dwordx2 s[2:3], s[0:1], 0x18
	s_load_dwordx2 s[100:101], s[0:1], 0x20
	s_load_dwordx2 s[12:13], s[0:1], 0x10
	s_mov_b32 s22, 0x0
	s_mov_b32 s23, 0x0
	s_mov_b32 s34, 0x5800000
	s_movk_i32 s6, 0x1600
	s_movk_i32 s7, 0x800
	s_movk_i32 s8, 0x2100
	s_mov_b32 s9, 1
	s_mov_b32 s10, 0
	s_mov_b32 s11, 1
	s_mov_b32 s24, 0x0
	s_mov_b32 s25, 32
	s_mov_b32 s26, 0
	s_movk_i32 s36, 0xb00
	s_movk_i32 s99, 0xb00
	s_branch .Lcv_common
.Lcv_par_3:
	s_load_dwordx2 s[2:3], s[0:1], 0x30
	s_load_dwordx2 s[12:13], s[0:1], 0x10
	s_mov_b32 s22, 0
	s_mov_b32 s23, 0x8400000
	s_mov_b32 s34, 0
	s_movk_i32 s6, 0x1000
	s_movk_i32 s7, 0x800
	s_movk_i32 s8, 0x800
	s_mov_b32 s9, 0
	s_mov_b32 s10, 0
	s_mov_b32 s11, 1
	s_mov_b32 s24, 0x2000
	s_mov_b32 s25, 32
	s_movk_i32 s26, 0x0
	s_mov_b32 s36, 0
	s_mov_b32 s99, 0x7fffffff
	s_branch .Lcv_common
.Lcv_par_4:
	s_load_dwordx2 s[2:3], s[0:1], 0x50
	s_mov_b32 s22, 0
	s_mov_b32 s23, 0x9c00000
	s_mov_b32 s34, 0
	s_movk_i32 s6, 0x800
	s_movk_i32 s7, 0x800
	s_movk_i32 s8, 0x400
	s_mov_b32 s9, 0
	s_mov_b32 s10, 0
	s_mov_b32 s11, 0
	s_mov_b32 s24, 0x0
	s_mov_b32 s25, 32
	s_movk_i32 s26, 0x0
	s_mov_b32 s36, 0
	s_mov_b32 s99, 0x7fffffff
	s_branch .Lcv_common
.Lcv_par_5:
	s_load_dwordx2 s[32:33], s[0:1], 0x28
	s_load_dwordx2 s[2:3], s[0:1], 0x18
	s_load_dwordx2 s[100:101], s[0:1], 0x20
	s_load_dwordx2 s[12:13], s[0:1], 0x10
	s_mov_b32 s22, 0x2c00000
	s_mov_b32 s23, 0x2c00000
	s_mov_b32 s34, 0x6e00000
	s_movk_i32 s6, 0x1600
	s_movk_i32 s7, 0x800
	s_movk_i32 s8, 0x2100
	s_mov_b32 s9, 1
	s_mov_b32 s10, 0
	s_mov_b32 s11, 1
	s_mov_b32 s24, 0x4000
	s_mov_b32 s25, 32
	s_mov_b32 s26, 0
	s_movk_i32 s36, 0xb00
	s_movk_i32 s99, 0xb00
	s_branch .Lcv_common
.Lcv_par_8:
	s_load_dwordx2 s[32:33], s[0:1], 0x28
	s_load_dwordx2 s[2:3], s[0:1], 0x18
	s_load_dwordx2 s[100:101], s[0:1], 0x20
	s_load_dwordx2 s[12:13], s[0:1], 0x10
	s_mov_b32 s22, 0x5800000
	s_mov_b32 s23, 0x0
	s_mov_b32 s34, 0x5800000
	s_movk_i32 s6, 0x1600
	s_movk_i32 s7, 0x800
	s_movk_i32 s8, 0x2100
	s_mov_b32 s9, 1
	s_mov_b32 s10, 0
	s_mov_b32 s11, 1
	s_mov_b32 s24, 0x6000
	s_mov_b32 s25, 32
	s_mov_b32 s26, 0
	s_movk_i32 s36, 0xb00
	s_movk_i32 s99, 0xb00
	s_branch .Lcv_common
.Lcv_par_11:
	s_load_dwordx2 s[2:3], s[0:1], 0x58
	s_load_dwordx2 s[12:13], s[0:1], 0x10
	s_mov_b32 s22, 0
	s_mov_b32 s23, 0x8400000
	s_mov_b32 s34, 0
	s_movk_i32 s6, 0x1800
	s_movk_i32 s7, 0x800
	s_movk_i32 s8, 0xc00
	s_mov_b32 s9, 2
	s_mov_b32 s10, 0
	s_mov_b32 s11, 1
	s_mov_b32 s24, 0x8000
	s_mov_b32 s25, 32
	s_movk_i32 s26, 0x1000
	s_mov_b32 s36, 0
	s_mov_b32 s99, 0x7fffffff
	s_branch .Lcv_common
.Lcv_par_12:
	s_load_dwordx2 s[2:3], s[0:1], 0x60
	s_mov_b32 s22, 0
	s_mov_b32 s23, 0x9c00000
	s_mov_b32 s34, 0
	s_movk_i32 s6, 0x800
	s_movk_i32 s7, 0x800
	s_movk_i32 s8, 0x400
	s_mov_b32 s9, 0
	s_mov_b32 s10, 0
	s_mov_b32 s11, 0
	s_mov_b32 s24, 0x0
	s_mov_b32 s25, 32
	s_movk_i32 s26, 0x0
	s_mov_b32 s36, 0
	s_mov_b32 s99, 0x7fffffff
	s_branch .Lcv_common
.Lcv_par_13:
	s_load_dwordx2 s[32:33], s[0:1], 0x28
	s_load_dwordx2 s[2:3], s[0:1], 0x18
	s_load_dwordx2 s[100:101], s[0:1], 0x20
	s_load_dwordx2 s[12:13], s[0:1], 0x10
	s_mov_b32 s22, 0x8400000
	s_mov_b32 s23, 0x2c00000
	s_mov_b32 s34, 0x6e00000
	s_movk_i32 s6, 0x1600
	s_movk_i32 s7, 0x800
	s_movk_i32 s8, 0x2100
	s_mov_b32 s9, 1
	s_mov_b32 s10, 0
	s_mov_b32 s11, 1
	s_mov_b32 s24, 0xa000
	s_mov_b32 s25, 32
	s_mov_b32 s26, 0
	s_movk_i32 s36, 0xb00
	s_movk_i32 s99, 0xb00
	s_branch .Lcv_common
; __device__ __forceinline__ void convert_w(LAS float* tile, const float* __restrict__ src, int K, int N, bf16_t* __restrict__ dst, int mode, int sidx, const float* __restrict__ gk, int G, int bid) {
;     const int tid = threadIdx.x;
;     const int tk = K / 64, tn = N / 64, ntile = tk * tn;
;     const int kk = tid >> 4, n4 = (tid & 15) * 4;
;     f32x4 pv[2];
;     if (bid < ntile) {
;         const int k0 = (bid % tk) * 64, n0 = (bid / tk) * 64;
; #pragma unroll
;         for (int i = 0; i < 2; ++i) pv[i] = __builtin_nontemporal_load((const f32x4*)(src + (size_t)(k0 + kk + 32 * i) * N + n0 + n4));
;     }
.Lcv_common:
	s_waitcnt lgkmcnt(0)
	s_add_u32 s2, s2, s22
	s_addc_u32 s3, s3, 0
	s_add_u32 s100, s100, s22
	s_addc_u32 s101, s101, 0
	s_add_u32 s32, s32, s22
	s_addc_u32 s33, s33, 0
	s_add_u32 s4, s82, s23
	s_addc_u32 s5, s83, 0
	s_add_u32 s34, s82, s34
	s_addc_u32 s35, s83, 0
	s_add_u32 s12, s12, s24
	s_addc_u32 s13, s13, 0
	s_mov_b32 s27, s26
	s_mov_b32 s16, s78
	s_lshl_b32 s17, s78, 1
	s_mov_b32 s14, s79
	v_lshrrev_b32_e32 v0, 4, v224
	v_and_b32_e32 v1, 15, v224
	v_lshlrev_b32_e32 v1, 2, v1
	v_mul_lo_u32 v2, v0, s6
	v_add_lshl_u32 v2, v2, v1, 2
	s_lshl_b32 s22, s6, 7
	v_add_u32_e32 v3, s22, v2
	v_mul_u32_u24_e32 v4, 0x41, v0
	v_add_lshl_u32 v4, v4, v1, 2
	v_add_u32_e32 v5, 0x2080, v4
	v_add_u32_e32 v6, 0x2088, v4
	v_lshrrev_b32_e32 v7, 3, v224
	v_and_b32_e32 v8, 7, v224
	v_lshlrev_b32_e32 v8, 3, v8
	v_mul_u32_u24_e32 v9, 0x41, v8
	v_add_lshl_u32 v9, v9, v7, 2
	v_add_u32_e32 v10, 0x400, v9
	v_mul_lo_u32 v11, v7, s7
	v_add_lshl_u32 v11, v11, v8, 1
	v_bfe_u32 v12, v7, 2, 2
	v_lshlrev_b32_e32 v12, 3, v12
	v_bfe_u32 v13, v7, 4, 1
	v_lshl_or_b32 v12, v13, 2, v12
	v_and_b32_e32 v13, 3, v7
	v_or_b32_e32 v12, v12, v13
	v_cmp_gt_u32_e32 vcc, 32, v7
	s_nop 1
	v_cndmask_b32_e32 v12, v7, v12, vcc
	v_mul_lo_u32 v12, v12, s7
	v_add_lshl_u32 v12, v12, v8, 1
	v_lshlrev_b32_e32 v14, 2, v8
	v_add_u32_e32 v14, 0x10000, v14
	v_lshlrev_b32_e32 v13, 4, v224
	v_add_u32_e32 v13, 0x10000, v13
	v_lshlrev_b32_e32 v56, 11, v0
	v_add_lshl_u32 v56, v56, v1, 2
	v_add_u32_e32 v57, 0x40000, v56
	s_movk_i32 s22, 0x1600
	v_mul_lo_u32 v58, v7, s22
	v_add_lshl_u32 v58, v58, v8, 1
	s_cmp_eq_u32 s11, 0
	s_cbranch_scc1 .Lcv_nogk0
	v_lshlrev_b32_e32 v15, 4, v224
	global_load_dwordx4 v[48:51], v15, s[12:13]
.Lcv_nogk0:
	s_mov_b32 s15, s14
	s_cmp_ge_u32 s15, s8
	s_cbranch_scc1 .Lcv_pro_done
	s_cmp_lt_u32 s15, s36
	s_cbranch_scc1 .Lcv_la_1
	s_sub_u32 s31, s15, s36
	s_cmp_ge_u32 s31, s99
	s_cselect_b32 s18, s100, s2
	s_cselect_b32 s19, s101, s3
	s_cselect_b32 s30, s99, 0
	s_sub_u32 s31, s31, s30
	s_lshr_b32 s28, s31, 5
	s_mul_hi_u32 s29, s31, 0x2e8ba2e9
	s_lshr_b32 s29, s29, 4
	s_cmpk_eq_u32 s7, 0x1600
	s_cselect_b32 s28, s29, s28
	s_mul_i32 s29, s28, s25
	s_sub_u32 s29, s31, s29
	s_lshl_b32 s30, s6, 8
	s_mul_i32 s30, s29, s30
	s_lshl_b32 s31, s28, 8
	s_add_u32 s30, s30, s31
	s_add_u32 s18, s18, s30
	s_addc_u32 s19, s19, 0
	global_load_dwordx4 v[16:19], v2, s[18:19] nt
	global_load_dwordx4 v[20:23], v3, s[18:19] nt
	s_branch .Lcv_lj_1
.Lcv_la_1:
	s_mul_hi_u32 s28, s15, 0x2e8ba2e9
	s_lshr_b32 s28, s28, 4
	s_mul_i32 s29, s28, 88
	s_sub_u32 s29, s15, s29
	s_lshl_b32 s30, s29, 19
	s_lshl_b32 s31, s28, 8
	s_add_u32 s30, s30, s31
	s_add_u32 s18, s32, s30
	s_addc_u32 s19, s33, 0
	global_load_dwordx4 v[16:19], v56, s[18:19] nt
	global_load_dwordx4 v[20:23], v57, s[18:19] nt
.Lcv_lj_1:
	s_add_u32 s15, s15, s16
	s_cmp_ge_u32 s15, s8
	s_cbranch_scc1 .Lcv_pro_done
	s_cmp_lt_u32 s15, s36
	s_cbranch_scc1 .Lcv_la_2
	s_sub_u32 s31, s15, s36
	s_cmp_ge_u32 s31, s99
	s_cselect_b32 s18, s100, s2
	s_cselect_b32 s19, s101, s3
	s_cselect_b32 s30, s99, 0
	s_sub_u32 s31, s31, s30
	s_lshr_b32 s28, s31, 5
	s_mul_hi_u32 s29, s31, 0x2e8ba2e9
	s_lshr_b32 s29, s29, 4
	s_cmpk_eq_u32 s7, 0x1600
	s_cselect_b32 s28, s29, s28
	s_mul_i32 s29, s28, s25
	s_sub_u32 s29, s31, s29
	s_lshl_b32 s30, s6, 8
	s_mul_i32 s30, s29, s30
	s_lshl_b32 s31, s28, 8
	s_add_u32 s30, s30, s31
	s_add_u32 s18, s18, s30
	s_addc_u32 s19, s19, 0
	global_load_dwordx4 v[24:27], v2, s[18:19] nt
	global_load_dwordx4 v[28:31], v3, s[18:19] nt
	s_branch .Lcv_lj_2
.Lcv_la_2:
	s_mul_hi_u32 s28, s15, 0x2e8ba2e9
	s_lshr_b32 s28, s28, 4
	s_mul_i32 s29, s28, 88
	s_sub_u32 s29, s15, s29
	s_lshl_b32 s30, s29, 19
	s_lshl_b32 s31, s28, 8
	s_add_u32 s30, s30, s31
	s_add_u32 s18, s32, s30
	s_addc_u32 s19, s33, 0
	global_load_dwordx4 v[24:27], v56, s[18:19] nt
	global_load_dwordx4 v[28:31], v57, s[18:19] nt
.Lcv_lj_2:
	s_add_u32 s15, s15, s16
	s_cmp_ge_u32 s15, s8
	s_cbranch_scc1 .Lcv_pro_done
	s_cmp_lt_u32 s15, s36
	s_cbranch_scc1 .Lcv_la_3
	s_sub_u32 s31, s15, s36
	s_cmp_ge_u32 s31, s99
	s_cselect_b32 s18, s100, s2
	s_cselect_b32 s19, s101, s3
	s_cselect_b32 s30, s99, 0
	s_sub_u32 s31, s31, s30
	s_lshr_b32 s28, s31, 5
	s_mul_hi_u32 s29, s31, 0x2e8ba2e9
	s_lshr_b32 s29, s29, 4
	s_cmpk_eq_u32 s7, 0x1600
	s_cselect_b32 s28, s29, s28
	s_mul_i32 s29, s28, s25
	s_sub_u32 s29, s31, s29
	s_lshl_b32 s30, s6, 8
	s_mul_i32 s30, s29, s30
	s_lshl_b32 s31, s28, 8
	s_add_u32 s30, s30, s31
	s_add_u32 s18, s18, s30
	s_addc_u32 s19, s19, 0
	global_load_dwordx4 v[32:35], v2, s[18:19] nt
	global_load_dwordx4 v[36:39], v3, s[18:19] nt
	s_branch .Lcv_lj_3
.Lcv_la_3:
	s_mul_hi_u32 s28, s15, 0x2e8ba2e9
	s_lshr_b32 s28, s28, 4
	s_mul_i32 s29, s28, 88
	s_sub_u32 s29, s15, s29
	s_lshl_b32 s30, s29, 19
	s_lshl_b32 s31, s28, 8
	s_add_u32 s30, s30, s31
	s_add_u32 s18, s32, s30
	s_addc_u32 s19, s33, 0
	global_load_dwordx4 v[32:35], v56, s[18:19] nt
	global_load_dwordx4 v[36:39], v57, s[18:19] nt
.Lcv_lj_3:
	s_add_u32 s15, s15, s16

; __device__ __forceinline__ unsigned cvt_pk_bf16(float lo, float hi) { unsigned r; asm volatile("v_cvt_pk_bf16_f32 %0, %1, %2" : "=v"(r) : "v"(lo), "v"(hi)); return r; }
; __device__ __forceinline__ void convert_w(LAS float* tile, const float* __restrict__ src, int K, int N, bf16_t* __restrict__ dst, int mode, int sidx, const float* __restrict__ gk, int G, int bid) {
;     ...
;     for (int t = bid; t < ntile; t += G) {
;         const int k0 = (t % tk) * 64, n0 = (t / tk) * 64;
; #pragma unroll
;         for (int i = 0; i < 2; ++i) {
;             const int k = kk + 32 * i;
;             tile[k * 65 + n4 + 0] = pv[i][0]; tile[k * 65 + n4 + 1] = pv[i][1]; tile[k * 65 + n4 + 2] = pv[i][2]; tile[k * 65 + n4 + 3] = pv[i][3];
;         }
;         __syncthreads();
;         if (t + G < ntile) {
;             const int k1 = ((t + G) % tk) * 64, n1 = ((t + G) / tk) * 64;
; #pragma unroll
;             for (int i = 0; i < 2; ++i) pv[i] = __builtin_nontemporal_load((const f32x4*)(src + (size_t)(k1 + kk + 32 * i) * N + n1 + n4));
;         }
;         const int n = tid >> 3, k8 = (tid & 7) * 8;
;         float f[8];
; #pragma unroll
;         for (int j = 0; j < 8; ++j) f[j] = tile[(k8 + j) * 65 + n];
;         if (gk) {
;             const f32x4 ga = *(const f32x4*)(gk + k0 + k8), gb = *(const f32x4*)(gk + k0 + k8 + 4);
;             f[0] *= ga[0]; f[1] *= ga[1]; f[2] *= ga[2]; f[3] *= ga[3]; f[4] *= gb[0]; f[5] *= gb[1]; f[6] *= gb[2]; f[7] *= gb[3];
;         }
;         u32x4 w; w.x = cvt_pk_bf16(f[0], f[1]); w.y = cvt_pk_bf16(f[2], f[3]); w.z = cvt_pk_bf16(f[4], f[5]); w.w = cvt_pk_bf16(f[6], f[7]);
;         const int nn = n0 + n;
;         int row = nn;
;         if (mode == 1) row = 256 * (nn >> 7) + 128 * sidx + (nn & 127);
;         if (mode == 2 && nn < 4096 && (nn & 127) < 32) { const int d = nn & 31; row = (nn & ~31) + 8 * ((d >> 2) & 3) + 4 * (d >> 4) + (d & 3); }
.Lcv_go_p0:
	ds_write2_b32 v4, v16, v17 offset1:1
	ds_write2_b32 v4, v18, v19 offset0:2 offset1:3
	ds_write2_b32 v5, v20, v21 offset1:1
	ds_write2_b32 v6, v22, v23 offset1:1
	s_waitcnt lgkmcnt(0)
	s_barrier
	s_add_u32 s23, s22, s16
	s_cmp_ge_u32 s23, s8
	s_cbranch_scc1 .Lcv_nold_p0
	s_cmp_lt_u32 s23, s36
	s_cbranch_scc1 .Lcv_la_4
	s_sub_u32 s31, s23, s36
	s_cmp_ge_u32 s31, s99
	s_cselect_b32 s18, s100, s2
	s_cselect_b32 s19, s101, s3
	s_cselect_b32 s30, s99, 0
	s_sub_u32 s31, s31, s30
	s_lshr_b32 s28, s31, 5
	s_mul_hi_u32 s29, s31, 0x2e8ba2e9
	s_lshr_b32 s29, s29, 4
	s_cmpk_eq_u32 s7, 0x1600
	s_cselect_b32 s28, s29, s28
	s_mul_i32 s29, s28, s25
	s_sub_u32 s29, s31, s29
	s_lshl_b32 s30, s6, 8
	s_mul_i32 s30, s29, s30
	s_lshl_b32 s31, s28, 8
	s_add_u32 s30, s30, s31
	s_add_u32 s18, s18, s30
	s_addc_u32 s19, s19, 0
	global_load_dwordx4 v[16:19], v2, s[18:19] nt
	global_load_dwordx4 v[20:23], v3, s[18:19] nt
	s_branch .Lcv_lj_4
.Lcv_la_4:
	s_mul_hi_u32 s28, s23, 0x2e8ba2e9
	s_lshr_b32 s28, s28, 4
	s_mul_i32 s29, s28, 88
	s_sub_u32 s29, s23, s29
	s_lshl_b32 s30, s29, 19
	s_lshl_b32 s31, s28, 8
	s_add_u32 s30, s30, s31
	s_add_u32 s18, s32, s30
	s_addc_u32 s19, s33, 0
	global_load_dwordx4 v[16:19], v56, s[18:19] nt
	global_load_dwordx4 v[20:23], v57, s[18:19] nt
.Lcv_lj_4:
.Lcv_nold_p0:
	ds_read2_b32 v[40:41], v9 offset1:65
	ds_read2_b32 v[42:43], v9 offset0:130 offset1:195
	ds_read2_b32 v[44:45], v10 offset0:4 offset1:69
	ds_read2_b32 v[46:47], v10 offset0:134 offset1:199
	s_cmp_lt_u32 s14, s36
	s_cbranch_scc1 .Lcv_sa_p0
	s_sub_u32 s31, s14, s36
	s_cmp_ge_u32 s31, s99
	s_cselect_b32 s30, s99, 0
	s_cselect_b32 s22, 0x80, 0
	s_sub_u32 s31, s31, s30
	s_lshr_b32 s28, s31, 5
	s_mul_hi_u32 s29, s31, 0x2e8ba2e9
	s_lshr_b32 s29, s29, 4
	s_cmpk_eq_u32 s7, 0x1600
	s_cselect_b32 s28, s29, s28
	s_mul_i32 s29, s28, s25
	s_sub_u32 s29, s31, s29
	s_cmp_eq_u32 s11, 0
	s_cbranch_scc1 .Lcv_nogkr_p0
	s_lshl_b32 s30, s29, 8
	v_add_u32_e32 v15, s30, v14
	ds_read_b128 v[48:51], v15
	ds_read_b128 v[52:55], v15 offset:16
.Lcv_nogkr_p0:
	s_lshl_b32 s30, s28, 6
	s_andn2_b32 s31, s30, 0x7f
	s_lshl_b32 s31, s31, 1
	s_and_b32 s23, s30, 64
	s_add_u32 s31, s31, s23
	s_add_u32 s31, s31, s10
	s_add_u32 s31, s31, s22
	s_cmp_eq_u32 s9, 1
	s_cselect_b32 s31, s31, s30
	s_mul_i32 s31, s31, s7
	s_lshl_b32 s31, s31, 1
	s_lshl_b32 s23, s29, 7
	s_add_u32 s31, s31, s23
	s_add_u32 s20, s4, s31
	s_addc_u32 s21, s5, 0
	s_waitcnt lgkmcnt(0)
	s_cmp_eq_u32 s11, 0
	s_cbranch_scc1 .Lcv_nomul_p0
	v_pk_mul_f32 v[40:41], v[40:41], v[48:49]
	v_pk_mul_f32 v[42:43], v[42:43], v[50:51]
	v_pk_mul_f32 v[44:45], v[44:45], v[52:53]
	v_pk_mul_f32 v[46:47], v[46:47], v[54:55]

; __device__ __forceinline__ unsigned cvt_pk_bf16(float lo, float hi) { unsigned r; asm volatile("v_cvt_pk_bf16_f32 %0, %1, %2" : "=v"(r) : "v"(lo), "v"(hi)); return r; }
; __device__ __forceinline__ void convert_w(LAS float* tile, const float* __restrict__ src, int K, int N, bf16_t* __restrict__ dst, int mode, int sidx, const float* __restrict__ gk, int G, int bid) {
;     ...
;         u32x4 w; w.x = cvt_pk_bf16(f[0], f[1]); w.y = cvt_pk_bf16(f[2], f[3]); w.z = cvt_pk_bf16(f[4], f[5]); w.w = cvt_pk_bf16(f[6], f[7]);
;         const int nn = n0 + n;
;         int row = nn;
;         if (mode == 1) row = 256 * (nn >> 7) + 128 * sidx + (nn & 127);
;         if (mode == 2 && nn < 4096 && (nn & 127) < 32) { const int d = nn & 31; row = (nn & ~31) + 8 * ((d >> 2) & 3) + 4 * (d >> 4) + (d & 3); }
;         *(u32x4*)(dst + (size_t)row * K + k0 + k8) = w;
.Lcv_perm_p0:
	global_store_dwordx4 v12, v[40:43], s[20:21]
	s_branch .Lcv_std_p0
.Lcv_sa_p0:
	s_mul_hi_u32 s28, s14, 0x2e8ba2e9
	s_lshr_b32 s28, s28, 4
	s_mul_i32 s29, s28, 88
	s_sub_u32 s29, s14, s29
	s_mul_i32 s31, s28, 0xb0000
	s_lshl_b32 s23, s29, 7
	s_add_u32 s31, s31, s23
	s_add_u32 s20, s34, s31
	s_addc_u32 s21, s35, 0
	s_waitcnt lgkmcnt(0)
	v_cvt_pk_bf16_f32 v40, v40, v41
	v_cvt_pk_bf16_f32 v41, v42, v43
	v_cvt_pk_bf16_f32 v42, v44, v45
	v_cvt_pk_bf16_f32 v43, v46, v47
	global_store_dwordx4 v58, v[40:43], s[20:21]

; __device__ __forceinline__ void convert_w(LAS float* tile, const float* __restrict__ src, int K, int N, bf16_t* __restrict__ dst, int mode, int sidx, const float* __restrict__ gk, int G, int bid) {
;     ...
;         if (t + G < ntile) {
;             const int k1 = ((t + G) % tk) * 64, n1 = ((t + G) / tk) * 64;
; #pragma unroll
;             for (int i = 0; i < 2; ++i) pv[i] = __builtin_nontemporal_load((const f32x4*)(src + (size_t)(k1 + kk + 32 * i) * N + n1 + n4));
;         }
.Lcv_go_p1:
	ds_write2_b32 v4, v24, v25 offset1:1
	ds_write2_b32 v4, v26, v27 offset0:2 offset1:3
	ds_write2_b32 v5, v28, v29 offset1:1
	ds_write2_b32 v6, v30, v31 offset1:1
	s_waitcnt lgkmcnt(0)
	s_barrier
	s_add_u32 s23, s22, s16
	s_cmp_ge_u32 s23, s8
	s_cbranch_scc1 .Lcv_nold_p1
	s_cmp_lt_u32 s23, s36
	s_cbranch_scc1 .Lcv_la_5
	s_sub_u32 s31, s23, s36
	s_cmp_ge_u32 s31, s99
	s_cselect_b32 s18, s100, s2
	s_cselect_b32 s19, s101, s3
	s_cselect_b32 s30, s99, 0
	s_sub_u32 s31, s31, s30
	s_lshr_b32 s28, s31, 5
	s_mul_hi_u32 s29, s31, 0x2e8ba2e9
	s_lshr_b32 s29, s29, 4
	s_cmpk_eq_u32 s7, 0x1600
	s_cselect_b32 s28, s29, s28
	s_mul_i32 s29, s28, s25
	s_sub_u32 s29, s31, s29
	s_lshl_b32 s30, s6, 8
	s_mul_i32 s30, s29, s30
	s_lshl_b32 s31, s28, 8
	s_add_u32 s30, s30, s31
	s_add_u32 s18, s18, s30
	s_addc_u32 s19, s19, 0
	global_load_dwordx4 v[24:27], v2, s[18:19] nt
	global_load_dwordx4 v[28:31], v3, s[18:19] nt
	s_branch .Lcv_lj_5
.Lcv_la_5:
	s_mul_hi_u32 s28, s23, 0x2e8ba2e9
	s_lshr_b32 s28, s28, 4
	s_mul_i32 s29, s28, 88
	s_sub_u32 s29, s23, s29
	s_lshl_b32 s30, s29, 19
	s_lshl_b32 s31, s28, 8
	s_add_u32 s30, s30, s31
	s_add_u32 s18, s32, s30
	s_addc_u32 s19, s33, 0
	global_load_dwordx4 v[24:27], v56, s[18:19] nt
	global_load_dwordx4 v[28:31], v57, s[18:19] nt

; __device__ __forceinline__ void convert_w(LAS float* tile, const float* __restrict__ src, int K, int N, bf16_t* __restrict__ dst, int mode, int sidx, const float* __restrict__ gk, int G, int bid) {
;     ...
;         if (t + G < ntile) {
;             const int k1 = ((t + G) % tk) * 64, n1 = ((t + G) / tk) * 64;
; #pragma unroll
;             for (int i = 0; i < 2; ++i) pv[i] = __builtin_nontemporal_load((const f32x4*)(src + (size_t)(k1 + kk + 32 * i) * N + n1 + n4));
;         }
.Lcv_go_p2:
	ds_write2_b32 v4, v32, v33 offset1:1
	ds_write2_b32 v4, v34, v35 offset0:2 offset1:3
	ds_write2_b32 v5, v36, v37 offset1:1
	ds_write2_b32 v6, v38, v39 offset1:1
	s_waitcnt lgkmcnt(0)
	s_barrier
	s_add_u32 s23, s22, s16
	s_cmp_ge_u32 s23, s8
	s_cbranch_scc1 .Lcv_nold_p2
	s_cmp_lt_u32 s23, s36
	s_cbranch_scc1 .Lcv_la_6
	s_sub_u32 s31, s23, s36
	s_cmp_ge_u32 s31, s99
	s_cselect_b32 s18, s100, s2
	s_cselect_b32 s19, s101, s3
	s_cselect_b32 s30, s99, 0
	s_sub_u32 s31, s31, s30
	s_lshr_b32 s28, s31, 5
	s_mul_hi_u32 s29, s31, 0x2e8ba2e9
	s_lshr_b32 s29, s29, 4
	s_cmpk_eq_u32 s7, 0x1600
	s_cselect_b32 s28, s29, s28
	s_mul_i32 s29, s28, s25
	s_sub_u32 s29, s31, s29
	s_lshl_b32 s30, s6, 8
	s_mul_i32 s30, s29, s30
	s_lshl_b32 s31, s28, 8
	s_add_u32 s30, s30, s31
	s_add_u32 s18, s18, s30
	s_addc_u32 s19, s19, 0
	global_load_dwordx4 v[32:35], v2, s[18:19] nt
	global_load_dwordx4 v[36:39], v3, s[18:19] nt
	s_branch .Lcv_lj_6
.Lcv_la_6:
	s_mul_hi_u32 s28, s23, 0x2e8ba2e9
	s_lshr_b32 s28, s28, 4
	s_mul_i32 s29, s28, 88
	s_sub_u32 s29, s23, s29
	s_lshl_b32 s30, s29, 19
	s_lshl_b32 s31, s28, 8
	s_add_u32 s30, s30, s31
	s_add_u32 s18, s32, s30
	s_addc_u32 s19, s33, 0
	global_load_dwordx4 v[32:35], v56, s[18:19] nt
	global_load_dwordx4 v[36:39], v57, s[18:19] nt

; __device__ __forceinline__ void convert_w(LAS float* tile, const float* __restrict__ src, int K, int N, bf16_t* __restrict__ dst, int mode, int sidx, const float* __restrict__ gk, int G, int bid) {
;     ...
;         __syncthreads();
;     }
.Lcv_done:
	s_waitcnt lgkmcnt(0)
	s_barrier
	v_readlane_b32 s0, v253, 0
	v_readlane_b32 s1, v253, 1
	v_readlane_b32 s2, v253, 2
	v_readlane_b32 s3, v253, 3
	v_readlane_b32 s4, v253, 4
	v_readlane_b32 s5, v253, 5
	v_readlane_b32 s6, v253, 6
	v_readlane_b32 s7, v253, 7
	v_readlane_b32 s8, v253, 8
	v_readlane_b32 s9, v253, 9
	v_readlane_b32 s10, v253, 10
	v_readlane_b32 s11, v253, 11
	v_readlane_b32 s12, v253, 12
	v_readlane_b32 s13, v253, 13
	v_readlane_b32 s14, v253, 14
	v_readlane_b32 s15, v253, 15
	v_readlane_b32 s16, v253, 16
	v_readlane_b32 s17, v253, 17
	v_readlane_b32 s18, v253, 18
	v_readlane_b32 s19, v253, 19
	v_readlane_b32 s20, v253, 20
	v_readlane_b32 s21, v253, 21
	v_readlane_b32 s22, v253, 22
	v_readlane_b32 s23, v253, 23
	v_readlane_b32 s24, v253, 24
	v_readlane_b32 s25, v253, 25
	v_readlane_b32 s26, v253, 26
	v_readlane_b32 s27, v253, 27
	v_readlane_b32 s28, v253, 28
	v_readlane_b32 s29, v253, 29
	v_readlane_b32 s30, v253, 30
	v_readlane_b32 s31, v253, 31
	v_readlane_b32 s32, v253, 32
	v_readlane_b32 s33, v253, 33
	v_readlane_b32 s34, v253, 34
	v_readlane_b32 s35, v253, 35
	v_readlane_b32 s36, v253, 36
	v_readlane_b32 s37, v253, 37
	v_readlane_b32 s38, v253, 38
	v_readlane_b32 s39, v253, 39
	s_nop 4
	s_cmp_eq_u32 s98, 0
	s_cbranch_scc1 .Lcv_ret_0
	s_cmp_eq_u32 s98, 3
	s_cbranch_scc1 .Lcv_ret_3
	s_cmp_eq_u32 s98, 4
	s_cbranch_scc1 .Lcv_ret_4
	s_cmp_eq_u32 s98, 5
	s_cbranch_scc1 .Lcv_ret_5
	s_cmp_eq_u32 s98, 8
	s_cbranch_scc1 .Lcv_ret_8
	s_cmp_eq_u32 s98, 11
	s_cbranch_scc1 .Lcv_ret_11
	s_cmp_eq_u32 s98, 12
	s_cbranch_scc1 .Lcv_ret_12
	s_cmp_eq_u32 s98, 13
	s_cbranch_scc1 .Lcv_ret_13
	s_branch .Lcv_ret_0

; #define LAS __attribute__((address_space(3)))
; __global__ void __launch_bounds__(NTHR, 2) mega_fwd(Params p) {
;     ...
;         convert_w((LAS float*)lds, p.w2 + (size_t)2 * WSZ, DFF, DM, W2, 0, 0, nullptr, G, bid);
;         convert_w((LAS float*)lds, p.w1 + (size_t)2 * WSZ, DM, DFF, W13, 1, 0, NG + 3 * DM, G, bid);
;         convert_w((LAS float*)lds, p.w3 + (size_t)2 * WSZ, DM, DFF, W13, 1, 1, NG + 3 * DM, G, bid);
.Lcv_site_p8:
	s_mov_b32 s98, 8
	s_branch .Lcv_entry
.Lcv_ret_8:
	s_mov_b64 s[0:1], -1

; #define LAS __attribute__((address_space(3)))
; __global__ void __launch_bounds__(NTHR, 2) mega_fwd(Params p) {
;     ...
;         convert_w((LAS float*)lds, p.w2 + (size_t)3 * WSZ, DFF, DM, W2 + (size_t)DM * DFF, 0, 0, nullptr, G, bid);
;         convert_w((LAS float*)lds, p.w1 + (size_t)3 * WSZ, DM, DFF, W13 + (size_t)2 * DFF * DM, 1, 0, NG + 5 * DM, G, bid);
;         convert_w((LAS float*)lds, p.w3 + (size_t)3 * WSZ, DM, DFF, W13 + (size_t)2 * DFF * DM, 1, 1, NG + 5 * DM, G, bid);
.Lcv_site_p15:
	s_mov_b32 s98, 13
	s_branch .Lcv_entry
.Lcv_ret_13:
	s_mov_b64 s[0:1], -1

; __global__ void __launch_bounds__(NTHR, 2) mega_fwd(Params p) {
	.amdhsa_kernel _Z8mega_fwd6Params
		.amdhsa_group_segment_fixed_size 0
		.amdhsa_private_segment_fixed_size 0
		.amdhsa_kernarg_size 456
		.amdhsa_user_sgpr_count 2
		.amdhsa_user_sgpr_dispatch_ptr 0
		.amdhsa_user_sgpr_queue_ptr 0
		.amdhsa_user_sgpr_kernarg_segment_ptr 1
		.amdhsa_user_sgpr_dispatch_id 0
		.amdhsa_user_sgpr_kernarg_preload_length 0
		.amdhsa_user_sgpr_kernarg_preload_offset 0
		.amdhsa_user_sgpr_private_segment_size 0
		.amdhsa_uses_dynamic_stack 0
		.amdhsa_enable_private_segment 0
		.amdhsa_system_sgpr_workgroup_id_x 1
		.amdhsa_system_sgpr_workgroup_id_y 0
		.amdhsa_system_sgpr_workgroup_id_z 0
		.amdhsa_system_sgpr_workgroup_info 0
		.amdhsa_system_vgpr_workitem_id 2
		.amdhsa_next_free_vgpr 255
		.amdhsa_next_free_sgpr 102
		.amdhsa_accum_offset 256
		.amdhsa_reserve_vcc 1
		.amdhsa_float_round_mode_32 0
		.amdhsa_float_round_mode_16_64 0
		.amdhsa_float_denorm_mode_32 3
		.amdhsa_float_denorm_mode_16_64 3
		.amdhsa_dx10_clamp 1
		.amdhsa_ieee_mode 1
		.amdhsa_fp16_overflow 0
		.amdhsa_tg_split 0
		.amdhsa_exception_fp_ieee_invalid_op 0
		.amdhsa_exception_fp_denorm_src 0
		.amdhsa_exception_fp_ieee_div_zero 0
		.amdhsa_exception_fp_ieee_overflow 0
		.amdhsa_exception_fp_ieee_underflow 0
		.amdhsa_exception_fp_ieee_inexact 0
		.amdhsa_exception_int_div_zero 0
	.end_amdhsa_kernel

; __global__ void __launch_bounds__(NTHR, 2) mega_fwd(Params p) {
amdhsa.kernels:
  - .agpr_count:     0
    .args:
      - .offset:         0
        .size:           200
        .value_kind:     by_value
      - .offset:         200
        .size:           4
        .value_kind:     hidden_block_count_x
      - .offset:         204
        .size:           4
        .value_kind:     hidden_block_count_y
      - .offset:         208
        .size:           4
        .value_kind:     hidden_block_count_z
      - .offset:         212
        .size:           2
        .value_kind:     hidden_group_size_x
      - .offset:         214
        .size:           2
        .value_kind:     hidden_group_size_y
      - .offset:         216
        .size:           2
        .value_kind:     hidden_group_size_z
      - .offset:         218
        .size:           2
        .value_kind:     hidden_remainder_x
      - .offset:         220
        .size:           2
        .value_kind:     hidden_remainder_y
      - .offset:         222
        .size:           2
        .value_kind:     hidden_remainder_z
      - .offset:         240
        .size:           8
        .value_kind:     hidden_global_offset_x
      - .offset:         248
        .size:           8
        .value_kind:     hidden_global_offset_y
      - .offset:         256
        .size:           8
        .value_kind:     hidden_global_offset_z
      - .offset:         264
        .size:           2
        .value_kind:     hidden_grid_dims
      - .offset:         288
        .size:           8
        .value_kind:     hidden_multigrid_sync_arg
      - .offset:         320
        .size:           4
        .value_kind:     hidden_dynamic_lds_size
    .group_segment_fixed_size: 0
    .kernarg_segment_align: 8
    .kernarg_segment_size: 456
    .language:       OpenCL C
    .language_version:
      - 2
      - 0
    .max_flat_workgroup_size: 512
    .name:           _Z8mega_fwd6Params
    .private_segment_fixed_size: 0
    .sgpr_count:     108
    .sgpr_spill_count: 148
    .symbol:         _Z8mega_fwd6Params.kd
    .uniform_work_group_size: 1
    .uses_dynamic_stack: false
    .vgpr_count:     255
    .vgpr_spill_count: 0
    .wavefront_size: 64
